# attn2 step loop: second K/V prefetch pair also decoupled (mask load before K/V in the second half, conditional counted waits at the first-half LDS write, second-half LDS write and back edge)
# baseline (speedup 1.0000x reference)
;     ...
;         auto lstore = [&](const u32x4 (&rg)[NJ], const float ckr, int stg) {
;             unsigned char* sb = lds + stg * STG;
; #pragma unroll
;             for (int j = 0; j < NJ; ++j) {
;                 if (j < NKJ) *(u32x4*)(sb + j * 9216 + lrow * 144 + lkc * 16) = rg[j];
;                 else { unsigned char* d = sb + VT_OFF + (lrow + 64 * (j - NKJ)) * 136 + lkc * 16; u32x2 a, c; a.x = rg[j].x; a.y = rg[j].y; c.x = rg[j].z; c.y = rg[j].w; *(u32x2*)d = a; *(u32x2*)(d + 8) = c; }
;             }
;             if (MODE == 1 && tid < 64) *(float*)(sb + CK_OFF + tid * 4) = ckr;
;         };
;     ...
;             if (DEEP) { if (kk + 3 < ntl) gload(rg_ld, ck_ld, kt + 3); } else { if (kk + 2 < ntl) gload(rg_ld, ck_ld, kt + 2); }
;             if (MODE == 2 && kk + 2 < ntl) wnext2 = mrow[kt + 2];
;             if (kk + 1 < ntl && (kt + 1) * 64 <= qw0 + 31) qk(s_nxt, mi_nxt, (kk + 1) % 3);
;             if (kt * 64 <= qw0 + 31) softmax_pv(s_cur, mi_cur, kt, kk % 3);
;             if (MODE == 2) { wcur = wnext; wnext = wnext2; }
;             if (kk + 2 < ntl) lstore(rg_st, ck_st, (kk + 2) % 3);
;             __syncthreads();
.LBB0_3618:
	s_or_b64 exec, exec, s[26:27]
	s_mul_hi_u32 s0, s47, 0xaaaaaaab
	s_lshr_b32 s0, s0, 1
	s_andn2_b64 vcc, exec, s[24:25]
	s_mul_i32 s0, s0, 0xd800
	s_cbranch_vccnz .LBB0_3620
	v_subrev_u32_e32 v1, s0, v203
	v_add_u32_e32 v4, s48, v200
	v_subrev_u32_e32 v2, s0, v197
	v_add_u32_e32 v1, v4, v1
	s_and_b64 vcc, exec, s[6:7]
	s_cbranch_vccz .Lvq_19t
	s_waitcnt vmcnt(4)
	ds_write_b128 v1, v[134:137]
	v_add3_u32 v1, v4, v2, s35
	s_waitcnt vmcnt(3)
	ds_write2_b64 v1, v[138:139], v[140:141] offset1:1
	s_branch .LBB0_3620
.Lvq_19t:
	s_waitcnt vmcnt(2)
	ds_write_b128 v1, v[134:137]
	v_add3_u32 v1, v4, v2, s35
	s_waitcnt vmcnt(1)
	ds_write2_b64 v1, v[138:139], v[140:141] offset1:1
.LBB0_3620:
	s_cmp_ge_i32 s52, s40
	s_waitcnt lgkmcnt(0)
	s_barrier
	s_cbranch_scc1 .LBB0_3631
	v_subrev_u32_e32 v211, s0, v204
	v_add_u32_e32 v211, s48, v211
	ds_read_b128 v[212:215], v211
	ds_read_b128 v[216:219], v211 offset:32
	ds_read_b128 v[220:223], v211 offset:64
	ds_read_b128 v[224:227], v211 offset:96
	ds_read_b128 v[228:231], v211 offset:4608
	ds_read_b128 v[232:235], v211 offset:4640
	ds_read_b128 v[236:239], v211 offset:4672
	ds_read_b128 v[240:243], v211 offset:4704
	s_and_b64 vcc, exec, s[6:7]
	s_cbranch_vccz .Lvq_mt
	s_waitcnt vmcnt(2)
	s_branch .Lmy_a2_w3join

;     ...
;         auto gload = [&](u32x4 (&rg)[NJ], float& ckr, int t) {
; #pragma unroll
;             for (int j = 0; j < NJ; ++j) rg[j] = *(const u32x4*)(src[j] + (size_t)t * step[j]);
;     ...
;             if (DEEP) { if (kk + 3 < ntl) gload(rg_ld, ck_ld, kt + 3); } else { if (kk + 2 < ntl) gload(rg_ld, ck_ld, kt + 2); }
.Lvq_kv:
	s_mov_b32 s55, 0
	s_cmp_ge_i32 s45, s40
	s_cbranch_scc1 .LBB0_3625
	v_lshl_add_u64 v[4:5], s[42:43], 0, v[186:187]
	v_add_co_u32_e32 v4, vcc, 0x73c0000, v4
	v_lshl_add_u64 v[6:7], s[42:43], 0, v[184:185]
	s_nop 0
	v_addc_co_u32_e32 v5, vcc, 0, v5, vcc
	v_add_co_u32_e32 v6, vcc, 0x15200000, v6
	s_nop 1
	v_addc_co_u32_e32 v7, vcc, 0, v7, vcc
	global_load_dwordx4 v[134:137], v[4:5], off offset:2048
	global_load_dwordx4 v[138:141], v[6:7], off offset:512
	s_mov_b32 s55, 1

;     ...
;         auto lstore = [&](const u32x4 (&rg)[NJ], const float ckr, int stg) {
;             unsigned char* sb = lds + stg * STG;
; #pragma unroll
;             for (int j = 0; j < NJ; ++j) {
;                 if (j < NKJ) *(u32x4*)(sb + j * 9216 + lrow * 144 + lkc * 16) = rg[j];
;                 else { unsigned char* d = sb + VT_OFF + (lrow + 64 * (j - NKJ)) * 136 + lkc * 16; u32x2 a, c; a.x = rg[j].x; a.y = rg[j].y; c.x = rg[j].z; c.y = rg[j].w; *(u32x2*)d = a; *(u32x2*)(d + 8) = c; }
;             }
;     ...
;             if (kk + 2 < ntl) lstore(rg_st, ck_st, (kk + 2) % 3);
.LBB0_3636:
	s_or_b64 exec, exec, s[24:25]
	s_and_b64 vcc, exec, s[4:5]
	s_cbranch_vccnz .LBB0_3638
	s_mul_hi_u32 s0, s46, 0xaaaaaaab
	s_lshr_b32 s0, s0, 1
	s_mul_i32 s0, s0, 0xd800
	v_subrev_u32_e32 v1, s0, v201
	v_add_u32_e32 v4, s48, v200
	v_subrev_u32_e32 v2, s0, v197
	v_add_u32_e32 v1, v4, v1
	s_cmp_lg_u32 s55, 0
	s_cbranch_scc0 .Lvq_37t
	s_waitcnt vmcnt(4)
	ds_write_b128 v1, v[158:161]
	v_add3_u32 v1, v4, v2, s36
	s_waitcnt vmcnt(3)
	ds_write2_b64 v1, v[162:163], v[164:165] offset1:1
	s_branch .LBB0_3638
.Lvq_37t:
	s_waitcnt vmcnt(2)
	ds_write_b128 v1, v[158:161]
	v_add3_u32 v1, v4, v2, s36
	s_waitcnt vmcnt(1)
	ds_write2_b64 v1, v[162:163], v[164:165] offset1:1

;     ...
;             if (MODE == 2) { wcur = wnext; wnext = wnext2; }
;     ...
;         for (int kk = 0; kk < ntl; kk += 2) {
;             if (DEEP) {
;                 stepf(sA, miA, sB, miB, rgE, ckrE, rgO, ckrO, kk);
;                 if (kk + 1 < ntl) stepf(sB, miB, sA, miA, rgO, ckrO, rgE, ckrE, kk + 1);
;             } else {
;                 stepf(sA, miA, sB, miB, rgE, ckrE, rgE, ckrE, kk);
;                 if (kk + 1 < ntl) stepf(sB, miB, sA, miA, rgE, ckrE, rgE, ckrE, kk + 1);
;             }
;         }
.LBB0_3639:
	s_add_i32 s45, s45, 2
	s_add_i32 s48, s48, 0x9000
	s_addk_i32 s44, 0x80
	s_add_i32 s41, s41, 2
	s_add_i32 s46, s46, 2
	s_add_i32 s47, s47, 2
	s_add_i32 s49, s49, 2
	v_lshl_add_u64 v[180:181], v[180:181], 0, 16
	v_lshl_add_u64 v[184:185], v[184:185], 0, s[18:19]
	s_cmp_ge_i32 s50, s40
	v_lshl_add_u64 v[186:187], v[186:187], 0, s[20:21]
	s_cbranch_scc1 .LBB0_3592
	s_cmp_lg_u32 s55, 0
	s_cbranch_scc0 .Lvq_bt
	s_waitcnt vmcnt(2)
	s_branch .Lvq_bj

;     ...
;             if (MODE == 2) { wcur = wnext; wnext = wnext2; }
;     ...
;         for (int kk = 0; kk < ntl; kk += 2) {
.Lvq_bj:
	v_mov_b64_e32 v[190:191], v[114:115]
	v_mov_b64_e32 v[192:193], v[114:115]
	s_branch .LBB0_3605
